# SSD out-proj epilogue: rstd rows staged in LDS instead of 32 serialized global loads
# speedup vs baseline: 1.0537x; 1.0029x over previous
.LBB0_2225:
	s_and_b32 s6, s2, 7
	v_lshl_add_u32 v0, s6, 8, v201
	v_ashrrev_i32_e32 v1, 31, v0
	v_lshlrev_b64 v[0:1], 12, v[0:1]
	s_and_b32 s6, s5, 0xffffff00
	v_lshl_add_u64 v[170:171], v[160:161], 0, v[0:1]
	v_add_u32_e32 v0, s6, v175
	s_and_b32 s6, s4, 7
	v_ashrrev_i32_e32 v1, 31, v0
	s_or_b32 s6, s6, s3
	v_lshlrev_b64 v[0:1], 12, v[0:1]
	s_lshl_b32 s6, s6, 8
	v_lshl_add_u64 v[172:173], v[168:169], 0, v[0:1]
	v_add_u32_e32 v0, s6, v175
	s_lshl_b32 s7, s4, 5
	v_ashrrev_i32_e32 v1, 31, v0
	s_and_b32 s7, s7, 0xffffff00
	v_add_u32_e32 v2, s7, v175
	v_lshlrev_b64 v[0:1], 12, v[0:1]
	s_waitcnt vmcnt(0) lgkmcnt(0)
	s_barrier
	v_and_b32_e32 v238, 0xff, v163
	v_add_u32_e32 v239, s6, v238
	v_lshlrev_b32_e32 v239, 2, v239
	global_load_dword v239, v239, s[0:1]
	v_lshlrev_b32_e32 v238, 2, v238
	v_add_u32_e32 v238, 0x20020, v238
	v_mov_b32_e32 v250, 0x20020
	v_ashrrev_i32_e32 v3, 31, v2
	v_lshl_add_u64 v[0:1], v[154:155], 0, v[0:1]
	v_readfirstlane_b32 s8, v180
	s_mov_b32 m0, s8
	s_nop 0
	global_load_lds_dwordx4 v[0:1], off
	s_mov_b64 s[12:13], 0x80000
	v_lshlrev_b64 v[2:3], 12, v[2:3]
	v_lshl_add_u64 v[4:5], v[0:1], 0, s[12:13]
	s_add_i32 s9, s8, 0x2000
	s_mov_b32 m0, s9
	s_nop 0
	global_load_lds_dwordx4 v[4:5], off
	v_lshl_add_u64 v[2:3], v[156:157], 0, v[2:3]
	s_add_i32 s9, s8, 0x4000
	s_mov_b32 m0, s9
	s_nop 0
	global_load_lds_dwordx4 v[2:3], off
	v_lshl_add_u64 v[4:5], v[2:3], 0, s[12:13]
	s_add_i32 s9, s8, 0x6000
	s_mov_b32 m0, s9
	s_nop 0
	global_load_lds_dwordx4 v[4:5], off
	s_add_i32 s9, s8, 0x8000
	v_lshl_add_u64 v[4:5], v[0:1], 0, 64
	s_mov_b32 m0, s9
	s_nop 0
	global_load_lds_dwordx4 v[4:5], off
	s_mov_b64 s[10:11], 0x80040
	v_lshl_add_u64 v[4:5], v[0:1], 0, s[10:11]
	s_add_i32 s9, s8, 0xa000
	s_mov_b32 m0, s9
	s_nop 0
	global_load_lds_dwordx4 v[4:5], off
	v_lshl_add_u64 v[4:5], v[2:3], 0, 64
	s_add_i32 s9, s8, 0xc000
	s_mov_b32 m0, s9
	s_nop 0
	global_load_lds_dwordx4 v[4:5], off
	v_lshl_add_u64 v[4:5], v[2:3], 0, s[10:11]
	s_add_i32 s9, s8, 0xe000
	s_mov_b32 m0, s9
	s_nop 0
	global_load_lds_dwordx4 v[4:5], off
	s_mov_b64 s[10:11], 0x80
	s_add_i32 s9, s8, 0x10000
	v_lshl_add_u64 v[4:5], v[0:1], 0, s[10:11]
	s_mov_b32 m0, s9
	s_nop 0
	global_load_lds_dwordx4 v[4:5], off
	s_mov_b64 s[14:15], 0x80080
	v_lshl_add_u64 v[0:1], v[0:1], 0, s[14:15]
	s_add_i32 s9, s8, 0x12000
	s_mov_b32 m0, s9
	s_nop 0
	global_load_lds_dwordx4 v[0:1], off
	v_lshl_add_u64 v[0:1], v[2:3], 0, s[10:11]
	s_add_i32 s9, s8, 0x14000
	s_mov_b32 m0, s9
	s_nop 0
	global_load_lds_dwordx4 v[0:1], off
	v_lshl_add_u64 v[0:1], v[2:3], 0, s[14:15]
	s_add_i32 s8, s8, 0x16000
	s_mov_b32 m0, s8
	s_nop 0
	global_load_lds_dwordx4 v[0:1], off
	s_waitcnt vmcnt(12)
	ds_write_b32 v238, v239
	v_mov_b32_e32 v130, 0
	v_mov_b32_e32 v134, 0
	v_mov_b32_e32 v0, 0
	s_mov_b32 s8, 0x18000
	v_mov_b32_e32 v1, v0
	v_mov_b32_e32 v2, v0
	v_mov_b32_e32 v3, v0
	v_mov_b32_e32 v4, v0
	v_mov_b32_e32 v5, v0
	v_mov_b32_e32 v6, v0
	v_mov_b32_e32 v7, v0
	v_mov_b32_e32 v8, v0
	v_mov_b32_e32 v9, v0
	v_mov_b32_e32 v10, v0
	v_mov_b32_e32 v11, v0
	v_mov_b32_e32 v12, v0
	v_mov_b32_e32 v13, v0
	v_mov_b32_e32 v14, v0
	v_mov_b32_e32 v15, v0
	v_mov_b32_e32 v16, v0
	v_mov_b32_e32 v17, v0
	v_mov_b32_e32 v18, v0
	v_mov_b32_e32 v19, v0
	v_mov_b32_e32 v20, v0
	v_mov_b32_e32 v21, v0
	v_mov_b32_e32 v22, v0
	v_mov_b32_e32 v23, v0
	v_mov_b32_e32 v24, v0
	v_mov_b32_e32 v25, v0
	v_mov_b32_e32 v26, v0
	v_mov_b32_e32 v27, v0
	v_mov_b32_e32 v28, v0
	v_mov_b32_e32 v29, v0
	v_mov_b32_e32 v30, v0
	v_mov_b32_e32 v31, v0
	v_mov_b32_e32 v32, v0
	v_mov_b32_e32 v33, v0
	v_mov_b32_e32 v34, v0
	v_mov_b32_e32 v35, v0
	v_mov_b32_e32 v36, v0
	v_mov_b32_e32 v37, v0
	v_mov_b32_e32 v38, v0
	v_mov_b32_e32 v39, v0
	v_mov_b32_e32 v40, v0
	v_mov_b32_e32 v41, v0
	v_mov_b32_e32 v42, v0
	v_mov_b32_e32 v43, v0
	v_mov_b32_e32 v44, v0
	v_mov_b32_e32 v45, v0
	v_mov_b32_e32 v46, v0
	v_mov_b32_e32 v47, v0
	v_mov_b32_e32 v48, v0
	v_mov_b32_e32 v49, v0
	v_mov_b32_e32 v50, v0
	v_mov_b32_e32 v51, v0
	v_mov_b32_e32 v52, v0
	v_mov_b32_e32 v53, v0
	v_mov_b32_e32 v54, v0
	v_mov_b32_e32 v55, v0
	v_mov_b32_e32 v56, v0
	v_mov_b32_e32 v57, v0
	v_mov_b32_e32 v58, v0
	v_mov_b32_e32 v59, v0
	v_mov_b32_e32 v60, v0
	v_mov_b32_e32 v61, v0
	v_mov_b32_e32 v62, v0
	v_mov_b32_e32 v63, v0
	v_mov_b32_e32 v64, v0
	v_mov_b32_e32 v65, v0
	v_mov_b32_e32 v66, v0
	v_mov_b32_e32 v67, v0
	v_mov_b32_e32 v68, v0
	v_mov_b32_e32 v69, v0
	v_mov_b32_e32 v70, v0
	v_mov_b32_e32 v71, v0
	v_mov_b32_e32 v72, v0
	v_mov_b32_e32 v73, v0
	v_mov_b32_e32 v74, v0
	v_mov_b32_e32 v75, v0
	v_mov_b32_e32 v76, v0
	v_mov_b32_e32 v77, v0
	v_mov_b32_e32 v78, v0
	v_mov_b32_e32 v79, v0
	v_mov_b32_e32 v80, v0
	v_mov_b32_e32 v81, v0
	v_mov_b32_e32 v82, v0
	v_mov_b32_e32 v83, v0
	v_mov_b32_e32 v84, v0
	v_mov_b32_e32 v85, v0
	v_mov_b32_e32 v86, v0
	v_mov_b32_e32 v87, v0
	v_mov_b32_e32 v88, v0
	v_mov_b32_e32 v89, v0
	v_mov_b32_e32 v90, v0
	v_mov_b32_e32 v91, v0
	v_mov_b32_e32 v92, v0
	v_mov_b32_e32 v93, v0
	v_mov_b32_e32 v94, v0
	v_mov_b32_e32 v95, v0
	v_mov_b32_e32 v96, v0
	v_mov_b32_e32 v97, v0
	v_mov_b32_e32 v98, v0
	v_mov_b32_e32 v99, v0
	v_mov_b32_e32 v100, v0
	v_mov_b32_e32 v101, v0
	v_mov_b32_e32 v102, v0
	v_mov_b32_e32 v103, v0
	v_mov_b32_e32 v104, v0
	v_mov_b32_e32 v105, v0
	v_mov_b32_e32 v106, v0
	v_mov_b32_e32 v107, v0
	v_mov_b32_e32 v108, v0
	v_mov_b32_e32 v109, v0
	v_mov_b32_e32 v110, v0
	v_mov_b32_e32 v111, v0
	v_mov_b32_e32 v112, v0
	v_mov_b32_e32 v113, v0
	v_mov_b32_e32 v114, v0
	v_mov_b32_e32 v115, v0
	v_mov_b32_e32 v116, v0
	v_mov_b32_e32 v117, v0
	v_mov_b32_e32 v118, v0
	v_mov_b32_e32 v119, v0
	v_mov_b32_e32 v120, v0
	v_mov_b32_e32 v121, v0
	v_mov_b32_e32 v122, v0
	v_mov_b32_e32 v123, v0
	v_mov_b32_e32 v124, v0
	v_mov_b32_e32 v125, v0
	v_mov_b32_e32 v126, v0
	v_mov_b32_e32 v127, v0
	v_mov_b32_e32 v135, v134
	v_mov_b32_e32 v136, v134
	v_mov_b32_e32 v137, v134
	v_mov_b32_e32 v138, v134
	v_mov_b32_e32 v139, v134
	v_mov_b32_e32 v140, v134
	v_mov_b32_e32 v141, v134
	v_mov_b32_e32 v146, v134
	v_mov_b32_e32 v147, v134
	v_mov_b32_e32 v148, v134
	v_mov_b32_e32 v149, v134
	v_mov_b32_e32 v150, v134
	v_mov_b32_e32 v151, v134
	v_mov_b32_e32 v152, v134
	v_mov_b32_e32 v153, v134
	v_mov_b32_e32 v131, v130
	v_mov_b32_e32 v132, v130
	v_mov_b32_e32 v133, v130
	v_mov_b32_e32 v142, v130
	v_mov_b32_e32 v143, v130
	v_mov_b32_e32 v144, v130
	v_mov_b32_e32 v145, v130
.LBB0_2226:
	s_and_b32 s9, s8, 0x18000
	v_add_u32_e32 v222, s9, v180
	s_add_i32 s9, s8, 0xfffe8000
	s_and_b32 s9, s9, 0x18000
	v_or_b32_e32 v223, s9, v179
	v_add_u32_e32 v233, s9, v176
	s_waitcnt vmcnt(8) lgkmcnt(0)
	s_barrier
	v_add_u32_e32 v206, v223, v177
	v_add_u32_e32 v234, v233, v177
	ds_read_b128 v[202:205], v206 offset:16384
	ds_read_b128 v[206:209], v206 offset:18432
	ds_read_b128 v[210:213], v234
	ds_read_b128 v[214:217], v234 offset:2048
	ds_read_b128 v[224:227], v234 offset:4096
	ds_read_b128 v[234:237], v234 offset:6144
	v_readfirstlane_b32 s9, v222
	s_mov_b32 m0, s9
	s_nop 0
	global_load_lds_dwordx4 v[170:171], off
	s_waitcnt lgkmcnt(9)
	v_mfma_f32_32x32x16_bf16 v[112:127], v[150:153], v[142:145], v[112:127]
	s_add_i32 s10, s9, 0x2000
	v_mfma_f32_32x32x16_bf16 v[96:111], v[150:153], v[130:133], v[96:111]
	v_lshl_add_u64 v[150:151], v[170:171], 0, s[12:13]
	s_mov_b32 m0, s10
	s_nop 0
	global_load_lds_dwordx4 v[150:151], off
	s_waitcnt lgkmcnt(8)
	v_mfma_f32_32x32x16_bf16 v[80:95], v[146:149], v[142:145], v[80:95]
	v_mfma_f32_32x32x16_bf16 v[64:79], v[146:149], v[130:133], v[64:79]
	s_waitcnt lgkmcnt(7)
	v_mfma_f32_32x32x16_bf16 v[48:63], v[138:141], v[142:145], v[48:63]
	v_mfma_f32_32x32x16_bf16 v[32:47], v[138:141], v[130:133], v[32:47]
	s_waitcnt lgkmcnt(6)
	v_mfma_f32_32x32x16_bf16 v[16:31], v[134:137], v[142:145], v[16:31]
	v_mfma_f32_32x32x16_bf16 v[0:15], v[134:137], v[130:133], v[0:15]
	v_add_u32_e32 v130, v223, v178
	v_add_u32_e32 v134, v233, v178
	ds_read_b128 v[142:145], v130 offset:16384
	ds_read_b128 v[130:133], v130 offset:18432
	ds_read_b128 v[150:153], v134
	ds_read_b128 v[146:149], v134 offset:2048
	ds_read_b128 v[138:141], v134 offset:4096
	ds_read_b128 v[134:137], v134 offset:6144
	s_waitcnt lgkmcnt(9)
	v_mfma_f32_32x32x16_bf16 v[112:127], v[210:213], v[202:205], v[112:127]
	s_add_i32 s10, s9, 0x6000
	s_addk_i32 s9, 0x4000
	s_mov_b32 m0, s9
	s_nop 0
	global_load_lds_dwordx4 v[172:173], off
	v_lshl_add_u64 v[222:223], v[172:173], 0, s[12:13]
	v_mfma_f32_32x32x16_bf16 v[96:111], v[210:213], v[206:209], v[96:111]
	s_waitcnt lgkmcnt(8)
	v_mfma_f32_32x32x16_bf16 v[80:95], v[214:217], v[202:205], v[80:95]
	s_mov_b32 m0, s10
	s_nop 0
	global_load_lds_dwordx4 v[222:223], off
	v_mfma_f32_32x32x16_bf16 v[64:79], v[214:217], v[206:209], v[64:79]
	s_waitcnt lgkmcnt(7)
	v_mfma_f32_32x32x16_bf16 v[48:63], v[224:227], v[202:205], v[48:63]
	v_mfma_f32_32x32x16_bf16 v[32:47], v[224:227], v[206:209], v[32:47]
	s_waitcnt lgkmcnt(6)
	v_mfma_f32_32x32x16_bf16 v[16:31], v[234:237], v[202:205], v[16:31]
	s_add_i32 s8, s8, 0x8000
	v_lshl_add_u64 v[170:171], v[170:171], 0, 64
	v_lshl_add_u64 v[172:173], v[172:173], 0, 64
	s_cmp_eq_u32 s8, 0x200000
	v_mfma_f32_32x32x16_bf16 v[0:15], v[234:237], v[206:209], v[0:15]
	s_cbranch_scc0 .LBB0_2226
	s_waitcnt vmcnt(8) lgkmcnt(0)
	s_barrier
	v_add_u32_e32 v202, v179, v177
	v_add_u32_e32 v222, v176, v177
	ds_read_b128 v[170:173], v202 offset:49152
	ds_read_b128 v[202:205], v202 offset:51200
	ds_read_b128 v[206:209], v222 offset:32768
	ds_read_b128 v[210:213], v222 offset:34816
	ds_read_b128 v[214:217], v222 offset:36864
	ds_read_b128 v[224:227], v222 offset:38912
	s_waitcnt lgkmcnt(9)
	v_mfma_f32_32x32x16_bf16 v[112:127], v[150:153], v[142:145], v[112:127]
	v_mfma_f32_32x32x16_bf16 v[96:111], v[150:153], v[130:133], v[96:111]
	s_waitcnt lgkmcnt(8)
	v_mfma_f32_32x32x16_bf16 v[80:95], v[146:149], v[142:145], v[80:95]
	v_mfma_f32_32x32x16_bf16 v[64:79], v[146:149], v[130:133], v[64:79]
	s_waitcnt lgkmcnt(7)
	v_mfma_f32_32x32x16_bf16 v[48:63], v[138:141], v[142:145], v[48:63]
	v_mfma_f32_32x32x16_bf16 v[32:47], v[138:141], v[130:133], v[32:47]
	s_waitcnt lgkmcnt(6)
	v_mfma_f32_32x32x16_bf16 v[16:31], v[134:137], v[142:145], v[16:31]
	v_mfma_f32_32x32x16_bf16 v[0:15], v[134:137], v[130:133], v[0:15]
	v_add_u32_e32 v134, v179, v178
	v_add_u32_e32 v150, v176, v178
	ds_read_b128 v[130:133], v134 offset:49152
	ds_read_b128 v[134:137], v134 offset:51200
	ds_read_b128 v[138:141], v150 offset:32768
	ds_read_b128 v[142:145], v150 offset:34816
	ds_read_b128 v[146:149], v150 offset:36864
	ds_read_b128 v[150:153], v150 offset:38912
	s_waitcnt lgkmcnt(9)
	v_mfma_f32_32x32x16_bf16 v[112:127], v[206:209], v[170:173], v[112:127]
	v_mfma_f32_32x32x16_bf16 v[96:111], v[206:209], v[202:205], v[96:111]
	s_waitcnt lgkmcnt(8)
	v_mfma_f32_32x32x16_bf16 v[80:95], v[210:213], v[170:173], v[80:95]
	v_mfma_f32_32x32x16_bf16 v[64:79], v[210:213], v[202:205], v[64:79]
	s_waitcnt lgkmcnt(7)
	v_mfma_f32_32x32x16_bf16 v[48:63], v[214:217], v[170:173], v[48:63]
	v_mfma_f32_32x32x16_bf16 v[32:47], v[214:217], v[202:205], v[32:47]
	s_waitcnt lgkmcnt(6)
	v_mfma_f32_32x32x16_bf16 v[0:15], v[224:227], v[202:205], v[0:15]
	s_waitcnt vmcnt(4) lgkmcnt(0)
	s_barrier
	v_add_u32_e32 v202, v199, v177
	v_add_u32_e32 v222, v200, v177
	v_mfma_f32_32x32x16_bf16 v[16:31], v[224:227], v[170:173], v[16:31]
	ds_read_b128 v[170:173], v202 offset:16384
	ds_read_b128 v[202:205], v202 offset:18432
	ds_read_b128 v[206:209], v222
	ds_read_b128 v[210:213], v222 offset:2048
	ds_read_b128 v[214:217], v222 offset:4096
	ds_read_b128 v[224:227], v222 offset:6144
	s_waitcnt lgkmcnt(9)
	v_mfma_f32_32x32x16_bf16 v[112:127], v[138:141], v[130:133], v[112:127]
	v_mfma_f32_32x32x16_bf16 v[96:111], v[138:141], v[134:137], v[96:111]
	s_waitcnt lgkmcnt(8)
	v_mfma_f32_32x32x16_bf16 v[80:95], v[142:145], v[130:133], v[80:95]
	v_mfma_f32_32x32x16_bf16 v[64:79], v[142:145], v[134:137], v[64:79]
	s_waitcnt lgkmcnt(7)
	v_mfma_f32_32x32x16_bf16 v[48:63], v[146:149], v[130:133], v[48:63]
	v_mfma_f32_32x32x16_bf16 v[32:47], v[146:149], v[134:137], v[32:47]
	s_waitcnt lgkmcnt(6)
	v_mfma_f32_32x32x16_bf16 v[16:31], v[150:153], v[130:133], v[16:31]
	v_mfma_f32_32x32x16_bf16 v[0:15], v[150:153], v[134:137], v[0:15]
	v_add_u32_e32 v134, v199, v178
	v_add_u32_e32 v150, v200, v178
	ds_read_b128 v[130:133], v134 offset:16384
	ds_read_b128 v[134:137], v134 offset:18432
	ds_read_b128 v[138:141], v150
	ds_read_b128 v[142:145], v150 offset:2048
	ds_read_b128 v[146:149], v150 offset:4096
	ds_read_b128 v[150:153], v150 offset:6144
	s_waitcnt lgkmcnt(9)
	v_mfma_f32_32x32x16_bf16 v[112:127], v[206:209], v[170:173], v[112:127]
	v_mfma_f32_32x32x16_bf16 v[96:111], v[206:209], v[202:205], v[96:111]
	s_waitcnt lgkmcnt(8)
	v_mfma_f32_32x32x16_bf16 v[80:95], v[210:213], v[170:173], v[80:95]
	v_mfma_f32_32x32x16_bf16 v[64:79], v[210:213], v[202:205], v[64:79]
	s_waitcnt lgkmcnt(7)
	v_mfma_f32_32x32x16_bf16 v[48:63], v[214:217], v[170:173], v[48:63]
	v_mfma_f32_32x32x16_bf16 v[32:47], v[214:217], v[202:205], v[32:47]
	s_waitcnt lgkmcnt(6)
	v_mfma_f32_32x32x16_bf16 v[0:15], v[224:227], v[202:205], v[0:15]
	s_waitcnt vmcnt(0) lgkmcnt(0)
	s_barrier
	v_add_u32_e32 v202, v197, v177
	v_add_u32_e32 v222, v198, v177
	v_mfma_f32_32x32x16_bf16 v[16:31], v[224:227], v[170:173], v[16:31]
	ds_read_b128 v[170:173], v202 offset:16384
	ds_read_b128 v[202:205], v202 offset:18432
	ds_read_b128 v[206:209], v222
	ds_read_b128 v[210:213], v222 offset:2048
	ds_read_b128 v[214:217], v222 offset:4096
	ds_read_b128 v[224:227], v222 offset:6144
	s_waitcnt lgkmcnt(9)
	v_mfma_f32_32x32x16_bf16 v[112:127], v[138:141], v[130:133], v[112:127]
	v_mfma_f32_32x32x16_bf16 v[96:111], v[138:141], v[134:137], v[96:111]
	s_waitcnt lgkmcnt(8)
	v_mfma_f32_32x32x16_bf16 v[80:95], v[142:145], v[130:133], v[80:95]
	v_mfma_f32_32x32x16_bf16 v[64:79], v[142:145], v[134:137], v[64:79]
	s_waitcnt lgkmcnt(7)
	v_mfma_f32_32x32x16_bf16 v[48:63], v[146:149], v[130:133], v[48:63]
	v_mfma_f32_32x32x16_bf16 v[32:47], v[146:149], v[134:137], v[32:47]
	s_waitcnt lgkmcnt(6)
	v_mfma_f32_32x32x16_bf16 v[16:31], v[150:153], v[130:133], v[16:31]
	v_mfma_f32_32x32x16_bf16 v[0:15], v[150:153], v[134:137], v[0:15]
	v_add_u32_e32 v134, v197, v178
	v_add_u32_e32 v150, v198, v178
	ds_read_b128 v[130:133], v134 offset:16384
	ds_read_b128 v[134:137], v134 offset:18432
	ds_read_b128 v[138:141], v150
	ds_read_b128 v[142:145], v150 offset:2048
	ds_read_b128 v[146:149], v150 offset:4096
	ds_read_b128 v[150:153], v150 offset:6144
	s_waitcnt lgkmcnt(9)
	v_mfma_f32_32x32x16_bf16 v[112:127], v[206:209], v[170:173], v[112:127]
	v_mfma_f32_32x32x16_bf16 v[96:111], v[206:209], v[202:205], v[96:111]
	s_waitcnt lgkmcnt(8)
	v_mfma_f32_32x32x16_bf16 v[80:95], v[210:213], v[170:173], v[80:95]
	v_mfma_f32_32x32x16_bf16 v[64:79], v[210:213], v[202:205], v[64:79]
	s_waitcnt lgkmcnt(7)
	v_mfma_f32_32x32x16_bf16 v[48:63], v[214:217], v[170:173], v[48:63]
	v_mfma_f32_32x32x16_bf16 v[32:47], v[214:217], v[202:205], v[32:47]
	s_waitcnt lgkmcnt(6)
	v_mfma_f32_32x32x16_bf16 v[16:31], v[224:227], v[170:173], v[16:31]
	v_mfma_f32_32x32x16_bf16 v[0:15], v[224:227], v[202:205], v[0:15]
	s_waitcnt lgkmcnt(3)
	v_mfma_f32_32x32x16_bf16 v[112:127], v[138:141], v[130:133], v[112:127]
	s_waitcnt lgkmcnt(2)
	v_mfma_f32_32x32x16_bf16 v[80:95], v[142:145], v[130:133], v[80:95]
	s_waitcnt lgkmcnt(1)
	v_mfma_f32_32x32x16_bf16 v[48:63], v[146:149], v[130:133], v[48:63]
	s_waitcnt lgkmcnt(0)
	v_mfma_f32_32x32x16_bf16 v[16:31], v[150:153], v[130:133], v[16:31]
	v_add_u32_e32 v132, s6, v174
	v_or_b32_e32 v130, s7, v128
	v_ashrrev_i32_e32 v131, 31, v130
	v_lshl_add_u64 v[130:131], v[130:131], 1, v[158:159]
	v_readlane_b32 s6, v252, 7
	s_add_i32 s4, s4, s6
	s_add_i32 s2, s2, s6
	v_mfma_f32_32x32x16_bf16 v[96:111], v[138:141], v[134:137], v[96:111]
	v_or_b32_e32 v138, v132, v181
	v_ashrrev_i32_e32 v139, 31, v138
	v_readlane_b32 s6, v252, 8
	s_add_i32 s5, s5, s6
	s_cmp_gt_i32 s4, 31
	v_mfma_f32_32x32x16_bf16 v[64:79], v[142:145], v[134:137], v[64:79]
	v_mfma_f32_32x32x16_bf16 v[32:47], v[146:149], v[134:137], v[32:47]
	v_mfma_f32_32x32x16_bf16 v[0:15], v[150:153], v[134:137], v[0:15]
	v_and_b32_e32 v134, 0xff, v138
	v_lshl_add_u32 v134, v134, 2, v250
	ds_read_b96 v[134:136], v134
	v_lshlrev_b64 v[138:139], 11, v[138:139]
	v_lshl_add_u64 v[138:139], v[130:131], 0, v[138:139]
	s_waitcnt lgkmcnt(0)
	v_mul_f32_e32 v112, v112, v134
	v_mul_f32_e32 v96, v96, v134
	v_cvt_pk_bf16_f32 v112, v112, s0
	v_cvt_pk_bf16_f32 v96, v96, s0
	global_store_short v[138:139], v112, off
	global_store_short v[138:139], v96, off offset:64
	v_or_b32_e32 v138, v132, v182
	v_ashrrev_i32_e32 v139, 31, v138
	v_lshlrev_b64 v[138:139], 11, v[138:139]
	v_mul_f32_e32 v96, v113, v135
	v_lshl_add_u64 v[138:139], v[130:131], 0, v[138:139]
	v_cvt_pk_bf16_f32 v96, v96, s0
	global_store_short v[138:139], v96, off
	v_mul_f32_e32 v96, v97, v135
	v_cvt_pk_bf16_f32 v96, v96, s0
	global_store_short v[138:139], v96, off offset:64
	v_or_b32_e32 v96, v132, v183
	v_ashrrev_i32_e32 v97, 31, v96
	v_lshlrev_b64 v[96:97], 11, v[96:97]
	v_mul_f32_e32 v112, v114, v136
	v_mul_f32_e32 v98, v98, v136
	v_lshl_add_u64 v[96:97], v[130:131], 0, v[96:97]
	v_cvt_pk_bf16_f32 v112, v112, s0
	v_cvt_pk_bf16_f32 v98, v98, s0
	global_store_short v[96:97], v112, off
	global_store_short v[96:97], v98, off offset:64
	v_or_b32_e32 v96, v132, v184
	v_ashrrev_i32_e32 v97, 31, v96
	v_and_b32_e32 v112, 0xff, v96
	v_lshl_add_u32 v112, v112, 2, v250
	ds_read_b32 v98, v112
	v_lshlrev_b64 v[96:97], 11, v[96:97]
	v_lshl_add_u64 v[96:97], v[130:131], 0, v[96:97]
	s_waitcnt lgkmcnt(0)
	v_mul_f32_e32 v112, v115, v98
	v_cvt_pk_bf16_f32 v112, v112, s0
	global_store_short v[96:97], v112, off
	v_mul_f32_e32 v98, v99, v98
	v_or_b32_e32 v112, v132, v185
	v_cvt_pk_bf16_f32 v98, v98, s0
	v_ashrrev_i32_e32 v113, 31, v112
	global_store_short v[96:97], v98, off offset:64
	v_and_b32_e32 v96, 0xff, v112
	v_lshl_add_u32 v96, v96, 2, v250
	ds_read_b96 v[96:98], v96
	v_lshlrev_b64 v[112:113], 11, v[112:113]
	v_lshl_add_u64 v[112:113], v[130:131], 0, v[112:113]
	s_waitcnt lgkmcnt(0)
	v_mul_f32_e32 v99, v116, v96
	v_mul_f32_e32 v96, v100, v96
	v_cvt_pk_bf16_f32 v99, v99, s0
	v_cvt_pk_bf16_f32 v96, v96, s0
	global_store_short v[112:113], v99, off
	global_store_short v[112:113], v96, off offset:64
	v_or_b32_e32 v112, v132, v186
	v_ashrrev_i32_e32 v113, 31, v112
	v_lshlrev_b64 v[112:113], 11, v[112:113]
	v_mul_f32_e32 v96, v117, v97
	v_lshl_add_u64 v[112:113], v[130:131], 0, v[112:113]
	v_cvt_pk_bf16_f32 v96, v96, s0
	global_store_short v[112:113], v96, off
	v_mul_f32_e32 v96, v101, v97
	v_cvt_pk_bf16_f32 v96, v96, s0
	global_store_short v[112:113], v96, off offset:64
	v_or_b32_e32 v96, v132, v187
	v_ashrrev_i32_e32 v97, 31, v96
	v_lshlrev_b64 v[96:97], 11, v[96:97]
	v_mul_f32_e32 v99, v118, v98
	v_mul_f32_e32 v98, v102, v98
	v_lshl_add_u64 v[96:97], v[130:131], 0, v[96:97]
	v_cvt_pk_bf16_f32 v99, v99, s0
	v_cvt_pk_bf16_f32 v98, v98, s0
	global_store_short v[96:97], v99, off
	global_store_short v[96:97], v98, off offset:64
	v_or_b32_e32 v96, v132, v188
	v_ashrrev_i32_e32 v97, 31, v96
	v_and_b32_e32 v98, 0xff, v96
	v_lshl_add_u32 v98, v98, 2, v250
	ds_read_b32 v98, v98
	v_lshlrev_b64 v[96:97], 11, v[96:97]
	v_or_b32_e32 v100, v132, v189
	v_lshl_add_u64 v[96:97], v[130:131], 0, v[96:97]
	v_ashrrev_i32_e32 v101, 31, v100
	s_waitcnt lgkmcnt(0)
	v_mul_f32_e32 v99, v119, v98
	v_mul_f32_e32 v98, v103, v98
	v_cvt_pk_bf16_f32 v99, v99, s0
	v_cvt_pk_bf16_f32 v98, v98, s0
	global_store_short v[96:97], v99, off
	global_store_short v[96:97], v98, off offset:64
	v_and_b32_e32 v96, 0xff, v100
	v_lshl_add_u32 v96, v96, 2, v250
	ds_read_b96 v[96:98], v96
	v_lshlrev_b64 v[100:101], 11, v[100:101]
	v_lshl_add_u64 v[100:101], v[130:131], 0, v[100:101]
	s_waitcnt lgkmcnt(0)
	v_mul_f32_e32 v99, v120, v96
	v_mul_f32_e32 v96, v104, v96
	v_cvt_pk_bf16_f32 v99, v99, s0
	v_cvt_pk_bf16_f32 v96, v96, s0
	global_store_short v[100:101], v99, off
	global_store_short v[100:101], v96, off offset:64
	v_or_b32_e32 v100, v132, v190
	v_ashrrev_i32_e32 v101, 31, v100
	v_lshlrev_b64 v[100:101], 11, v[100:101]
	v_mul_f32_e32 v96, v121, v97
	v_lshl_add_u64 v[100:101], v[130:131], 0, v[100:101]
	v_cvt_pk_bf16_f32 v96, v96, s0
	global_store_short v[100:101], v96, off
	v_mul_f32_e32 v96, v105, v97
	v_cvt_pk_bf16_f32 v96, v96, s0
	global_store_short v[100:101], v96, off offset:64
	v_or_b32_e32 v96, v132, v191
	v_ashrrev_i32_e32 v97, 31, v96
	v_lshlrev_b64 v[96:97], 11, v[96:97]
	v_mul_f32_e32 v99, v122, v98
	v_mul_f32_e32 v98, v106, v98
	v_lshl_add_u64 v[96:97], v[130:131], 0, v[96:97]
	v_cvt_pk_bf16_f32 v99, v99, s0
	v_cvt_pk_bf16_f32 v98, v98, s0
	global_store_short v[96:97], v99, off
	global_store_short v[96:97], v98, off offset:64
	v_or_b32_e32 v96, v132, v192
	v_ashrrev_i32_e32 v97, 31, v96
	v_and_b32_e32 v98, 0xff, v96
	v_lshl_add_u32 v98, v98, 2, v250
	ds_read_b32 v98, v98
	v_lshlrev_b64 v[96:97], 11, v[96:97]
	v_or_b32_e32 v100, v132, v193
	v_lshl_add_u64 v[96:97], v[130:131], 0, v[96:97]
	v_ashrrev_i32_e32 v101, 31, v100
	s_waitcnt lgkmcnt(0)
	v_mul_f32_e32 v99, v123, v98
	v_mul_f32_e32 v98, v107, v98
	v_cvt_pk_bf16_f32 v99, v99, s0
	v_cvt_pk_bf16_f32 v98, v98, s0
	global_store_short v[96:97], v99, off
	global_store_short v[96:97], v98, off offset:64
	v_and_b32_e32 v96, 0xff, v100
	v_lshl_add_u32 v96, v96, 2, v250
	ds_read_b96 v[96:98], v96
	v_lshlrev_b64 v[100:101], 11, v[100:101]
	v_lshl_add_u64 v[100:101], v[130:131], 0, v[100:101]
	s_waitcnt lgkmcnt(0)
	v_mul_f32_e32 v99, v124, v96
	v_mul_f32_e32 v96, v108, v96
	v_cvt_pk_bf16_f32 v99, v99, s0
	v_cvt_pk_bf16_f32 v96, v96, s0
	global_store_short v[100:101], v99, off
	global_store_short v[100:101], v96, off offset:64
	v_or_b32_e32 v100, v132, v194
	v_ashrrev_i32_e32 v101, 31, v100
	v_lshlrev_b64 v[100:101], 11, v[100:101]
	v_mul_f32_e32 v96, v125, v97
	v_lshl_add_u64 v[100:101], v[130:131], 0, v[100:101]
	v_cvt_pk_bf16_f32 v96, v96, s0
	global_store_short v[100:101], v96, off
	v_mul_f32_e32 v96, v109, v97
	v_cvt_pk_bf16_f32 v96, v96, s0
	global_store_short v[100:101], v96, off offset:64
	v_or_b32_e32 v96, v132, v195
	v_ashrrev_i32_e32 v97, 31, v96
	v_lshlrev_b64 v[96:97], 11, v[96:97]
	v_mul_f32_e32 v99, v126, v98
	v_mul_f32_e32 v98, v110, v98
	v_lshl_add_u64 v[96:97], v[130:131], 0, v[96:97]
	v_cvt_pk_bf16_f32 v99, v99, s0
	v_cvt_pk_bf16_f32 v98, v98, s0
	global_store_short v[96:97], v99, off
	global_store_short v[96:97], v98, off offset:64
	v_or_b32_e32 v96, v132, v196
	v_ashrrev_i32_e32 v97, 31, v96
	v_and_b32_e32 v98, 0xff, v96
	v_lshl_add_u32 v98, v98, 2, v250
	ds_read_b32 v98, v98
	v_lshlrev_b64 v[96:97], 11, v[96:97]
	v_lshl_add_u64 v[96:97], v[130:131], 0, v[96:97]
	s_waitcnt lgkmcnt(0)
	v_mul_f32_e32 v99, v127, v98
	v_mul_f32_e32 v98, v111, v98
	v_cvt_pk_bf16_f32 v99, v99, s0
	v_cvt_pk_bf16_f32 v98, v98, s0
	global_store_short v[96:97], v99, off
	global_store_short v[96:97], v98, off offset:64
	v_or_b32_e32 v96, 32, v132
	v_or_b32_e32 v102, v96, v181
	v_ashrrev_i32_e32 v103, 31, v102
	v_and_b32_e32 v98, 0xff, v102
	v_lshl_add_u32 v98, v98, 2, v250
	ds_read_b96 v[98:100], v98
	v_lshlrev_b64 v[102:103], 11, v[102:103]
	v_lshl_add_u64 v[102:103], v[130:131], 0, v[102:103]
	s_waitcnt lgkmcnt(0)
	v_mul_f32_e32 v80, v80, v98
	v_mul_f32_e32 v64, v64, v98
	v_cvt_pk_bf16_f32 v80, v80, s0
	v_cvt_pk_bf16_f32 v64, v64, s0
	global_store_short v[102:103], v80, off
	global_store_short v[102:103], v64, off offset:64
	v_or_b32_e32 v102, v96, v182
	v_ashrrev_i32_e32 v103, 31, v102
	v_lshlrev_b64 v[102:103], 11, v[102:103]
	v_mul_f32_e32 v64, v81, v99
	v_lshl_add_u64 v[102:103], v[130:131], 0, v[102:103]
	v_cvt_pk_bf16_f32 v64, v64, s0
	global_store_short v[102:103], v64, off
	v_mul_f32_e32 v64, v65, v99
	v_cvt_pk_bf16_f32 v64, v64, s0
	global_store_short v[102:103], v64, off offset:64
	v_or_b32_e32 v64, v96, v183
	v_ashrrev_i32_e32 v65, 31, v64
	v_lshlrev_b64 v[64:65], 11, v[64:65]
	v_mul_f32_e32 v80, v82, v100
	v_mul_f32_e32 v66, v66, v100
	v_lshl_add_u64 v[64:65], v[130:131], 0, v[64:65]
	v_cvt_pk_bf16_f32 v80, v80, s0
	v_cvt_pk_bf16_f32 v66, v66, s0
	global_store_short v[64:65], v80, off
	global_store_short v[64:65], v66, off offset:64
	v_or_b32_e32 v64, v96, v184
	v_ashrrev_i32_e32 v65, 31, v64
	v_and_b32_e32 v80, 0xff, v64
	v_lshl_add_u32 v80, v80, 2, v250
	ds_read_b32 v66, v80
	v_lshlrev_b64 v[64:65], 11, v[64:65]
	v_lshl_add_u64 v[64:65], v[130:131], 0, v[64:65]
	s_waitcnt lgkmcnt(0)
	v_mul_f32_e32 v80, v83, v66
	v_cvt_pk_bf16_f32 v80, v80, s0
	global_store_short v[64:65], v80, off
	v_mul_f32_e32 v66, v67, v66
	v_or_b32_e32 v80, v96, v185
	v_cvt_pk_bf16_f32 v66, v66, s0
	v_ashrrev_i32_e32 v81, 31, v80
	global_store_short v[64:65], v66, off offset:64
	v_and_b32_e32 v64, 0xff, v80
	v_lshl_add_u32 v64, v64, 2, v250
	ds_read_b96 v[64:66], v64
	v_lshlrev_b64 v[80:81], 11, v[80:81]
	v_lshl_add_u64 v[80:81], v[130:131], 0, v[80:81]
	s_waitcnt lgkmcnt(0)
	v_mul_f32_e32 v67, v84, v64
	v_mul_f32_e32 v64, v68, v64
	v_cvt_pk_bf16_f32 v67, v67, s0
	v_cvt_pk_bf16_f32 v64, v64, s0
	global_store_short v[80:81], v67, off
	global_store_short v[80:81], v64, off offset:64
	v_or_b32_e32 v80, v96, v186
	v_ashrrev_i32_e32 v81, 31, v80
	v_lshlrev_b64 v[80:81], 11, v[80:81]
	v_mul_f32_e32 v64, v85, v65
	v_lshl_add_u64 v[80:81], v[130:131], 0, v[80:81]
	v_cvt_pk_bf16_f32 v64, v64, s0
	global_store_short v[80:81], v64, off
	v_mul_f32_e32 v64, v69, v65
	v_cvt_pk_bf16_f32 v64, v64, s0
	global_store_short v[80:81], v64, off offset:64
	v_or_b32_e32 v64, v96, v187
	v_ashrrev_i32_e32 v65, 31, v64
	v_lshlrev_b64 v[64:65], 11, v[64:65]
	v_mul_f32_e32 v67, v86, v66
	v_mul_f32_e32 v66, v70, v66
	v_lshl_add_u64 v[64:65], v[130:131], 0, v[64:65]
	v_cvt_pk_bf16_f32 v67, v67, s0
	v_cvt_pk_bf16_f32 v66, v66, s0
	global_store_short v[64:65], v67, off
	global_store_short v[64:65], v66, off offset:64
	v_or_b32_e32 v64, v96, v188
	v_ashrrev_i32_e32 v65, 31, v64
	v_and_b32_e32 v66, 0xff, v64
	v_lshl_add_u32 v66, v66, 2, v250
	ds_read_b32 v66, v66
	v_lshlrev_b64 v[64:65], 11, v[64:65]
	v_or_b32_e32 v68, v96, v189
	v_lshl_add_u64 v[64:65], v[130:131], 0, v[64:65]
	v_ashrrev_i32_e32 v69, 31, v68
	s_waitcnt lgkmcnt(0)
	v_mul_f32_e32 v67, v87, v66
	v_mul_f32_e32 v66, v71, v66
	v_cvt_pk_bf16_f32 v67, v67, s0
	v_cvt_pk_bf16_f32 v66, v66, s0
	global_store_short v[64:65], v67, off
	global_store_short v[64:65], v66, off offset:64
	v_and_b32_e32 v64, 0xff, v68
	v_lshl_add_u32 v64, v64, 2, v250
	ds_read_b96 v[64:66], v64
	v_lshlrev_b64 v[68:69], 11, v[68:69]
	v_lshl_add_u64 v[68:69], v[130:131], 0, v[68:69]
	s_waitcnt lgkmcnt(0)
	v_mul_f32_e32 v67, v88, v64
	v_mul_f32_e32 v64, v72, v64
	v_cvt_pk_bf16_f32 v67, v67, s0
	v_cvt_pk_bf16_f32 v64, v64, s0
	global_store_short v[68:69], v67, off
	global_store_short v[68:69], v64, off offset:64
	v_or_b32_e32 v68, v96, v190
	v_ashrrev_i32_e32 v69, 31, v68
	v_lshlrev_b64 v[68:69], 11, v[68:69]
	v_mul_f32_e32 v64, v89, v65
	v_lshl_add_u64 v[68:69], v[130:131], 0, v[68:69]
	v_cvt_pk_bf16_f32 v64, v64, s0
	global_store_short v[68:69], v64, off
	v_mul_f32_e32 v64, v73, v65
	v_cvt_pk_bf16_f32 v64, v64, s0
	global_store_short v[68:69], v64, off offset:64
	v_or_b32_e32 v64, v96, v191
	v_ashrrev_i32_e32 v65, 31, v64
	v_lshlrev_b64 v[64:65], 11, v[64:65]
	v_mul_f32_e32 v67, v90, v66
	v_mul_f32_e32 v66, v74, v66
	v_lshl_add_u64 v[64:65], v[130:131], 0, v[64:65]
	v_cvt_pk_bf16_f32 v67, v67, s0
	v_cvt_pk_bf16_f32 v66, v66, s0
	global_store_short v[64:65], v67, off
	global_store_short v[64:65], v66, off offset:64
	v_or_b32_e32 v64, v96, v192
	v_ashrrev_i32_e32 v65, 31, v64
	v_and_b32_e32 v66, 0xff, v64
	v_lshl_add_u32 v66, v66, 2, v250
	ds_read_b32 v66, v66
	v_lshlrev_b64 v[64:65], 11, v[64:65]
	v_or_b32_e32 v68, v96, v193
	v_lshl_add_u64 v[64:65], v[130:131], 0, v[64:65]
	v_ashrrev_i32_e32 v69, 31, v68
	s_waitcnt lgkmcnt(0)
	v_mul_f32_e32 v67, v91, v66
	v_mul_f32_e32 v66, v75, v66
	v_cvt_pk_bf16_f32 v67, v67, s0
	v_cvt_pk_bf16_f32 v66, v66, s0
	global_store_short v[64:65], v67, off
	global_store_short v[64:65], v66, off offset:64
	v_and_b32_e32 v64, 0xff, v68
	v_lshl_add_u32 v64, v64, 2, v250
	ds_read_b96 v[64:66], v64
	v_lshlrev_b64 v[68:69], 11, v[68:69]
	v_lshl_add_u64 v[68:69], v[130:131], 0, v[68:69]
	s_waitcnt lgkmcnt(0)
	v_mul_f32_e32 v67, v92, v64
	v_mul_f32_e32 v64, v76, v64
	v_cvt_pk_bf16_f32 v67, v67, s0
	v_cvt_pk_bf16_f32 v64, v64, s0
	global_store_short v[68:69], v67, off
	global_store_short v[68:69], v64, off offset:64
	v_or_b32_e32 v68, v96, v194
	v_ashrrev_i32_e32 v69, 31, v68
	v_lshlrev_b64 v[68:69], 11, v[68:69]
	v_mul_f32_e32 v64, v93, v65
	v_lshl_add_u64 v[68:69], v[130:131], 0, v[68:69]
	v_cvt_pk_bf16_f32 v64, v64, s0
	global_store_short v[68:69], v64, off
	v_mul_f32_e32 v64, v77, v65
	v_cvt_pk_bf16_f32 v64, v64, s0
	global_store_short v[68:69], v64, off offset:64
	v_or_b32_e32 v64, v96, v195
	v_ashrrev_i32_e32 v65, 31, v64
	v_lshlrev_b64 v[64:65], 11, v[64:65]
	v_mul_f32_e32 v67, v94, v66
	v_mul_f32_e32 v66, v78, v66
	v_lshl_add_u64 v[64:65], v[130:131], 0, v[64:65]
	v_cvt_pk_bf16_f32 v67, v67, s0
	v_cvt_pk_bf16_f32 v66, v66, s0
	global_store_short v[64:65], v67, off
	global_store_short v[64:65], v66, off offset:64
	v_or_b32_e32 v64, v96, v196
	v_ashrrev_i32_e32 v65, 31, v64
	v_and_b32_e32 v66, 0xff, v64
	v_lshl_add_u32 v66, v66, 2, v250
	ds_read_b32 v66, v66
	v_lshlrev_b64 v[64:65], 11, v[64:65]
	v_lshl_add_u64 v[64:65], v[130:131], 0, v[64:65]
	s_waitcnt lgkmcnt(0)
	v_mul_f32_e32 v67, v95, v66
	v_mul_f32_e32 v66, v79, v66
	v_cvt_pk_bf16_f32 v67, v67, s0
	v_cvt_pk_bf16_f32 v66, v66, s0
	global_store_short v[64:65], v67, off
	global_store_short v[64:65], v66, off offset:64
	v_or_b32_e32 v64, 64, v132
	v_or_b32_e32 v70, v64, v181
	v_ashrrev_i32_e32 v71, 31, v70
	v_and_b32_e32 v66, 0xff, v70
	v_lshl_add_u32 v66, v66, 2, v250
	ds_read_b96 v[66:68], v66
	v_lshlrev_b64 v[70:71], 11, v[70:71]
	v_lshl_add_u64 v[70:71], v[130:131], 0, v[70:71]
	s_waitcnt lgkmcnt(0)
	v_mul_f32_e32 v48, v48, v66
	v_mul_f32_e32 v32, v32, v66
	v_cvt_pk_bf16_f32 v48, v48, s0
	v_cvt_pk_bf16_f32 v32, v32, s0
	global_store_short v[70:71], v48, off
	global_store_short v[70:71], v32, off offset:64
	v_or_b32_e32 v70, v64, v182
	v_ashrrev_i32_e32 v71, 31, v70
	v_lshlrev_b64 v[70:71], 11, v[70:71]
	v_mul_f32_e32 v32, v49, v67
	v_lshl_add_u64 v[70:71], v[130:131], 0, v[70:71]
	v_cvt_pk_bf16_f32 v32, v32, s0
	global_store_short v[70:71], v32, off
	v_mul_f32_e32 v32, v33, v67
	v_cvt_pk_bf16_f32 v32, v32, s0
	global_store_short v[70:71], v32, off offset:64
	v_or_b32_e32 v32, v64, v183
	v_ashrrev_i32_e32 v33, 31, v32
	v_lshlrev_b64 v[32:33], 11, v[32:33]
	v_mul_f32_e32 v48, v50, v68
	v_mul_f32_e32 v34, v34, v68
	v_lshl_add_u64 v[32:33], v[130:131], 0, v[32:33]
	v_cvt_pk_bf16_f32 v48, v48, s0
	v_cvt_pk_bf16_f32 v34, v34, s0
	global_store_short v[32:33], v48, off
	global_store_short v[32:33], v34, off offset:64
	v_or_b32_e32 v32, v64, v184
	v_ashrrev_i32_e32 v33, 31, v32
	v_and_b32_e32 v48, 0xff, v32
	v_lshl_add_u32 v48, v48, 2, v250
	ds_read_b32 v34, v48
	v_lshlrev_b64 v[32:33], 11, v[32:33]
	v_lshl_add_u64 v[32:33], v[130:131], 0, v[32:33]
	s_waitcnt lgkmcnt(0)
	v_mul_f32_e32 v48, v51, v34
	v_cvt_pk_bf16_f32 v48, v48, s0
	global_store_short v[32:33], v48, off
	v_mul_f32_e32 v34, v35, v34
	v_or_b32_e32 v48, v64, v185
	v_cvt_pk_bf16_f32 v34, v34, s0
	v_ashrrev_i32_e32 v49, 31, v48
	global_store_short v[32:33], v34, off offset:64
	v_and_b32_e32 v32, 0xff, v48
	v_lshl_add_u32 v32, v32, 2, v250
	ds_read_b96 v[32:34], v32
	v_lshlrev_b64 v[48:49], 11, v[48:49]
	v_lshl_add_u64 v[48:49], v[130:131], 0, v[48:49]
	s_waitcnt lgkmcnt(0)
	v_mul_f32_e32 v35, v52, v32
	v_mul_f32_e32 v32, v36, v32
	v_cvt_pk_bf16_f32 v35, v35, s0
	v_cvt_pk_bf16_f32 v32, v32, s0
	global_store_short v[48:49], v35, off
	global_store_short v[48:49], v32, off offset:64
	v_or_b32_e32 v48, v64, v186
	v_ashrrev_i32_e32 v49, 31, v48
	v_lshlrev_b64 v[48:49], 11, v[48:49]
	v_mul_f32_e32 v32, v53, v33
	v_lshl_add_u64 v[48:49], v[130:131], 0, v[48:49]
	v_cvt_pk_bf16_f32 v32, v32, s0
	global_store_short v[48:49], v32, off
	v_mul_f32_e32 v32, v37, v33
	v_cvt_pk_bf16_f32 v32, v32, s0
	global_store_short v[48:49], v32, off offset:64
	v_or_b32_e32 v32, v64, v187
	v_ashrrev_i32_e32 v33, 31, v32
	v_lshlrev_b64 v[32:33], 11, v[32:33]
	v_mul_f32_e32 v35, v54, v34
	v_mul_f32_e32 v34, v38, v34
	v_lshl_add_u64 v[32:33], v[130:131], 0, v[32:33]
	v_cvt_pk_bf16_f32 v35, v35, s0
	v_cvt_pk_bf16_f32 v34, v34, s0
	global_store_short v[32:33], v35, off
	global_store_short v[32:33], v34, off offset:64
	v_or_b32_e32 v32, v64, v188
	v_ashrrev_i32_e32 v33, 31, v32
	v_and_b32_e32 v34, 0xff, v32
	v_lshl_add_u32 v34, v34, 2, v250
	ds_read_b32 v34, v34
	v_lshlrev_b64 v[32:33], 11, v[32:33]
	v_or_b32_e32 v36, v64, v189
	v_lshl_add_u64 v[32:33], v[130:131], 0, v[32:33]
	v_ashrrev_i32_e32 v37, 31, v36
	s_waitcnt lgkmcnt(0)
	v_mul_f32_e32 v35, v55, v34
	v_mul_f32_e32 v34, v39, v34
	v_cvt_pk_bf16_f32 v35, v35, s0
	v_cvt_pk_bf16_f32 v34, v34, s0
	global_store_short v[32:33], v35, off
	global_store_short v[32:33], v34, off offset:64
	v_and_b32_e32 v32, 0xff, v36
	v_lshl_add_u32 v32, v32, 2, v250
	ds_read_b96 v[32:34], v32
	v_lshlrev_b64 v[36:37], 11, v[36:37]
	v_lshl_add_u64 v[36:37], v[130:131], 0, v[36:37]
	s_waitcnt lgkmcnt(0)
	v_mul_f32_e32 v35, v56, v32
	v_mul_f32_e32 v32, v40, v32
	v_cvt_pk_bf16_f32 v35, v35, s0
	v_cvt_pk_bf16_f32 v32, v32, s0
	global_store_short v[36:37], v35, off
	global_store_short v[36:37], v32, off offset:64
	v_or_b32_e32 v36, v64, v190
	v_ashrrev_i32_e32 v37, 31, v36
	v_lshlrev_b64 v[36:37], 11, v[36:37]
	v_mul_f32_e32 v32, v57, v33
	v_lshl_add_u64 v[36:37], v[130:131], 0, v[36:37]
	v_cvt_pk_bf16_f32 v32, v32, s0
	global_store_short v[36:37], v32, off
	v_mul_f32_e32 v32, v41, v33
	v_cvt_pk_bf16_f32 v32, v32, s0
	global_store_short v[36:37], v32, off offset:64
	v_or_b32_e32 v32, v64, v191
	v_ashrrev_i32_e32 v33, 31, v32
	v_lshlrev_b64 v[32:33], 11, v[32:33]
	v_mul_f32_e32 v35, v58, v34
	v_mul_f32_e32 v34, v42, v34
	v_lshl_add_u64 v[32:33], v[130:131], 0, v[32:33]
	v_cvt_pk_bf16_f32 v35, v35, s0
	v_cvt_pk_bf16_f32 v34, v34, s0
	global_store_short v[32:33], v35, off
	global_store_short v[32:33], v34, off offset:64
	v_or_b32_e32 v32, v64, v192
	v_ashrrev_i32_e32 v33, 31, v32
	v_and_b32_e32 v34, 0xff, v32
	v_lshl_add_u32 v34, v34, 2, v250
	ds_read_b32 v34, v34
	v_lshlrev_b64 v[32:33], 11, v[32:33]
	v_or_b32_e32 v36, v64, v193
	v_lshl_add_u64 v[32:33], v[130:131], 0, v[32:33]
	v_ashrrev_i32_e32 v37, 31, v36
	s_waitcnt lgkmcnt(0)
	v_mul_f32_e32 v35, v59, v34
	v_mul_f32_e32 v34, v43, v34
	v_cvt_pk_bf16_f32 v35, v35, s0
	v_cvt_pk_bf16_f32 v34, v34, s0
	global_store_short v[32:33], v35, off
	global_store_short v[32:33], v34, off offset:64
	v_and_b32_e32 v32, 0xff, v36
	v_lshl_add_u32 v32, v32, 2, v250
	ds_read_b96 v[32:34], v32
	v_lshlrev_b64 v[36:37], 11, v[36:37]
	v_lshl_add_u64 v[36:37], v[130:131], 0, v[36:37]
	s_waitcnt lgkmcnt(0)
	v_mul_f32_e32 v35, v60, v32
	v_mul_f32_e32 v32, v44, v32
	v_cvt_pk_bf16_f32 v35, v35, s0
	v_cvt_pk_bf16_f32 v32, v32, s0
	global_store_short v[36:37], v35, off
	global_store_short v[36:37], v32, off offset:64
	v_or_b32_e32 v36, v64, v194
	v_ashrrev_i32_e32 v37, 31, v36
	v_lshlrev_b64 v[36:37], 11, v[36:37]
	v_mul_f32_e32 v32, v61, v33
	v_lshl_add_u64 v[36:37], v[130:131], 0, v[36:37]
	v_cvt_pk_bf16_f32 v32, v32, s0
	global_store_short v[36:37], v32, off
	v_mul_f32_e32 v32, v45, v33
	v_cvt_pk_bf16_f32 v32, v32, s0
	global_store_short v[36:37], v32, off offset:64
	v_or_b32_e32 v32, v64, v195
	v_ashrrev_i32_e32 v33, 31, v32
	v_lshlrev_b64 v[32:33], 11, v[32:33]
	v_mul_f32_e32 v35, v62, v34
	v_mul_f32_e32 v34, v46, v34
	v_lshl_add_u64 v[32:33], v[130:131], 0, v[32:33]
	v_cvt_pk_bf16_f32 v35, v35, s0
	v_cvt_pk_bf16_f32 v34, v34, s0
	global_store_short v[32:33], v35, off
	global_store_short v[32:33], v34, off offset:64
	v_or_b32_e32 v32, v64, v196
	v_ashrrev_i32_e32 v33, 31, v32
	v_and_b32_e32 v34, 0xff, v32
	v_lshl_add_u32 v34, v34, 2, v250
	ds_read_b32 v34, v34
	v_lshlrev_b64 v[32:33], 11, v[32:33]
	v_lshl_add_u64 v[32:33], v[130:131], 0, v[32:33]
	s_waitcnt lgkmcnt(0)
	v_mul_f32_e32 v35, v63, v34
	v_mul_f32_e32 v34, v47, v34
	v_cvt_pk_bf16_f32 v35, v35, s0
	v_cvt_pk_bf16_f32 v34, v34, s0
	global_store_short v[32:33], v35, off
	global_store_short v[32:33], v34, off offset:64
	v_or_b32_e32 v32, 0x60, v132
	v_or_b32_e32 v38, v32, v181
	v_ashrrev_i32_e32 v39, 31, v38
	v_and_b32_e32 v34, 0xff, v38
	v_lshl_add_u32 v34, v34, 2, v250
	ds_read_b96 v[34:36], v34
	v_lshlrev_b64 v[38:39], 11, v[38:39]
	v_lshl_add_u64 v[38:39], v[130:131], 0, v[38:39]
	s_waitcnt lgkmcnt(0)
	v_mul_f32_e32 v16, v16, v34
	v_mul_f32_e32 v0, v0, v34
	v_cvt_pk_bf16_f32 v16, v16, s0
	v_cvt_pk_bf16_f32 v0, v0, s0
	global_store_short v[38:39], v16, off
	global_store_short v[38:39], v0, off offset:64
	v_or_b32_e32 v38, v32, v182
	v_ashrrev_i32_e32 v39, 31, v38
	v_lshlrev_b64 v[38:39], 11, v[38:39]
	v_mul_f32_e32 v0, v17, v35
	v_lshl_add_u64 v[38:39], v[130:131], 0, v[38:39]
	v_cvt_pk_bf16_f32 v0, v0, s0
	global_store_short v[38:39], v0, off
	v_mul_f32_e32 v0, v1, v35
	v_cvt_pk_bf16_f32 v0, v0, s0
	global_store_short v[38:39], v0, off offset:64
	v_or_b32_e32 v0, v32, v183
	v_ashrrev_i32_e32 v1, 31, v0
	v_lshlrev_b64 v[0:1], 11, v[0:1]
	v_mul_f32_e32 v16, v18, v36
	v_mul_f32_e32 v2, v2, v36
	v_lshl_add_u64 v[0:1], v[130:131], 0, v[0:1]
	v_cvt_pk_bf16_f32 v16, v16, s0
	v_cvt_pk_bf16_f32 v2, v2, s0
	global_store_short v[0:1], v16, off
	global_store_short v[0:1], v2, off offset:64
	v_or_b32_e32 v0, v32, v184
	v_ashrrev_i32_e32 v1, 31, v0
	v_and_b32_e32 v16, 0xff, v0
	v_lshl_add_u32 v16, v16, 2, v250
	ds_read_b32 v2, v16
	v_lshlrev_b64 v[0:1], 11, v[0:1]
	v_lshl_add_u64 v[0:1], v[130:131], 0, v[0:1]
	s_waitcnt lgkmcnt(0)
	v_mul_f32_e32 v16, v19, v2
	v_cvt_pk_bf16_f32 v16, v16, s0
	global_store_short v[0:1], v16, off
	v_mul_f32_e32 v2, v3, v2
	v_or_b32_e32 v16, v32, v185
	v_cvt_pk_bf16_f32 v2, v2, s0
	v_ashrrev_i32_e32 v17, 31, v16
	global_store_short v[0:1], v2, off offset:64
	v_and_b32_e32 v0, 0xff, v16
	v_lshl_add_u32 v0, v0, 2, v250
	ds_read_b96 v[0:2], v0
	v_lshlrev_b64 v[16:17], 11, v[16:17]
	v_lshl_add_u64 v[16:17], v[130:131], 0, v[16:17]
	s_waitcnt lgkmcnt(0)
	v_mul_f32_e32 v3, v20, v0
	v_mul_f32_e32 v0, v4, v0
	v_cvt_pk_bf16_f32 v3, v3, s0
	v_cvt_pk_bf16_f32 v0, v0, s0
	global_store_short v[16:17], v3, off
	global_store_short v[16:17], v0, off offset:64
	v_or_b32_e32 v16, v32, v186
	v_ashrrev_i32_e32 v17, 31, v16
	v_lshlrev_b64 v[16:17], 11, v[16:17]
	v_mul_f32_e32 v0, v21, v1
	v_lshl_add_u64 v[16:17], v[130:131], 0, v[16:17]
	v_cvt_pk_bf16_f32 v0, v0, s0
	global_store_short v[16:17], v0, off
	v_mul_f32_e32 v0, v5, v1
	v_cvt_pk_bf16_f32 v0, v0, s0
	global_store_short v[16:17], v0, off offset:64
	v_or_b32_e32 v0, v32, v187
	v_ashrrev_i32_e32 v1, 31, v0
	v_lshlrev_b64 v[0:1], 11, v[0:1]
	v_mul_f32_e32 v3, v22, v2
	v_mul_f32_e32 v2, v6, v2
	v_lshl_add_u64 v[0:1], v[130:131], 0, v[0:1]
	v_cvt_pk_bf16_f32 v3, v3, s0
	v_cvt_pk_bf16_f32 v2, v2, s0
	global_store_short v[0:1], v3, off
	global_store_short v[0:1], v2, off offset:64
	v_or_b32_e32 v0, v32, v188
	v_ashrrev_i32_e32 v1, 31, v0
	v_and_b32_e32 v2, 0xff, v0
	v_lshl_add_u32 v2, v2, 2, v250
	ds_read_b32 v2, v2
	v_lshlrev_b64 v[0:1], 11, v[0:1]
	v_or_b32_e32 v4, v32, v189
	v_lshl_add_u64 v[0:1], v[130:131], 0, v[0:1]
	v_ashrrev_i32_e32 v5, 31, v4
	s_waitcnt lgkmcnt(0)
	v_mul_f32_e32 v3, v23, v2
	v_mul_f32_e32 v2, v7, v2
	v_cvt_pk_bf16_f32 v3, v3, s0
	v_cvt_pk_bf16_f32 v2, v2, s0
	global_store_short v[0:1], v3, off
	global_store_short v[0:1], v2, off offset:64
	v_and_b32_e32 v0, 0xff, v4
	v_lshl_add_u32 v0, v0, 2, v250
	ds_read_b96 v[0:2], v0
	v_lshlrev_b64 v[4:5], 11, v[4:5]
	v_lshl_add_u64 v[4:5], v[130:131], 0, v[4:5]
	s_waitcnt lgkmcnt(0)
	v_mul_f32_e32 v3, v24, v0
	v_mul_f32_e32 v0, v8, v0
	v_cvt_pk_bf16_f32 v3, v3, s0
	v_cvt_pk_bf16_f32 v0, v0, s0
	global_store_short v[4:5], v3, off
	global_store_short v[4:5], v0, off offset:64
	v_or_b32_e32 v4, v32, v190
	v_ashrrev_i32_e32 v5, 31, v4
	v_lshlrev_b64 v[4:5], 11, v[4:5]
	v_mul_f32_e32 v0, v25, v1
	v_lshl_add_u64 v[4:5], v[130:131], 0, v[4:5]
	v_cvt_pk_bf16_f32 v0, v0, s0
	global_store_short v[4:5], v0, off
	v_mul_f32_e32 v0, v9, v1
	v_cvt_pk_bf16_f32 v0, v0, s0
	global_store_short v[4:5], v0, off offset:64
	v_or_b32_e32 v0, v32, v191
	v_ashrrev_i32_e32 v1, 31, v0
	v_lshlrev_b64 v[0:1], 11, v[0:1]
	v_mul_f32_e32 v3, v26, v2
	v_mul_f32_e32 v2, v10, v2
	v_lshl_add_u64 v[0:1], v[130:131], 0, v[0:1]
	v_cvt_pk_bf16_f32 v3, v3, s0
	v_cvt_pk_bf16_f32 v2, v2, s0
	global_store_short v[0:1], v3, off
	global_store_short v[0:1], v2, off offset:64
	v_or_b32_e32 v0, v32, v192
	v_ashrrev_i32_e32 v1, 31, v0
	v_and_b32_e32 v2, 0xff, v0
	v_lshl_add_u32 v2, v2, 2, v250
	ds_read_b32 v2, v2
	v_lshlrev_b64 v[0:1], 11, v[0:1]
	v_or_b32_e32 v4, v32, v193
	v_lshl_add_u64 v[0:1], v[130:131], 0, v[0:1]
	v_ashrrev_i32_e32 v5, 31, v4
	s_waitcnt lgkmcnt(0)
	v_mul_f32_e32 v3, v27, v2
	v_mul_f32_e32 v2, v11, v2
	v_cvt_pk_bf16_f32 v3, v3, s0
	v_cvt_pk_bf16_f32 v2, v2, s0
	global_store_short v[0:1], v3, off
	global_store_short v[0:1], v2, off offset:64
	v_and_b32_e32 v0, 0xff, v4
	v_lshl_add_u32 v0, v0, 2, v250
	ds_read_b96 v[0:2], v0
	v_lshlrev_b64 v[4:5], 11, v[4:5]
	v_lshl_add_u64 v[4:5], v[130:131], 0, v[4:5]
	s_waitcnt lgkmcnt(0)
	v_mul_f32_e32 v3, v28, v0
	v_mul_f32_e32 v0, v12, v0
	v_cvt_pk_bf16_f32 v3, v3, s0
	v_cvt_pk_bf16_f32 v0, v0, s0
	global_store_short v[4:5], v3, off
	global_store_short v[4:5], v0, off offset:64
	v_or_b32_e32 v4, v32, v194
	v_ashrrev_i32_e32 v5, 31, v4
	v_lshlrev_b64 v[4:5], 11, v[4:5]
	v_mul_f32_e32 v0, v29, v1
	v_lshl_add_u64 v[4:5], v[130:131], 0, v[4:5]
	v_cvt_pk_bf16_f32 v0, v0, s0
	global_store_short v[4:5], v0, off
	v_mul_f32_e32 v0, v13, v1
	v_cvt_pk_bf16_f32 v0, v0, s0
	global_store_short v[4:5], v0, off offset:64
	v_or_b32_e32 v0, v32, v195
	v_ashrrev_i32_e32 v1, 31, v0
	v_lshlrev_b64 v[0:1], 11, v[0:1]
	v_mul_f32_e32 v3, v30, v2
	v_mul_f32_e32 v2, v14, v2
	v_lshl_add_u64 v[0:1], v[130:131], 0, v[0:1]
	v_cvt_pk_bf16_f32 v3, v3, s0
	v_cvt_pk_bf16_f32 v2, v2, s0
	global_store_short v[0:1], v3, off
	global_store_short v[0:1], v2, off offset:64
	v_or_b32_e32 v0, v32, v196
	v_ashrrev_i32_e32 v1, 31, v0
	v_and_b32_e32 v2, 0xff, v0
	v_lshl_add_u32 v2, v2, 2, v250
	ds_read_b32 v2, v2
	v_lshlrev_b64 v[0:1], 11, v[0:1]
	v_lshl_add_u64 v[0:1], v[130:131], 0, v[0:1]
	s_waitcnt lgkmcnt(0)
	v_mul_f32_e32 v3, v31, v2
	v_mul_f32_e32 v2, v15, v2
	v_cvt_pk_bf16_f32 v3, v3, s0
	v_cvt_pk_bf16_f32 v2, v2, s0
	global_store_short v[0:1], v3, off
	global_store_short v[0:1], v2, off offset:64
	s_cbranch_scc0 .LBB0_2225

	.amdhsa_kernel _Z4mega6Params
		.amdhsa_group_segment_fixed_size 132128
		.amdhsa_private_segment_fixed_size 0
		.amdhsa_kernarg_size 496
		.amdhsa_user_sgpr_count 2
		.amdhsa_user_sgpr_dispatch_ptr 0
		.amdhsa_user_sgpr_queue_ptr 0
		.amdhsa_user_sgpr_kernarg_segment_ptr 1
		.amdhsa_user_sgpr_dispatch_id 0
		.amdhsa_user_sgpr_kernarg_preload_length 0
		.amdhsa_user_sgpr_kernarg_preload_offset 0
		.amdhsa_user_sgpr_private_segment_size 0
		.amdhsa_uses_dynamic_stack 0
		.amdhsa_enable_private_segment 0
		.amdhsa_system_sgpr_workgroup_id_x 1
		.amdhsa_system_sgpr_workgroup_id_y 0
		.amdhsa_system_sgpr_workgroup_id_z 0
		.amdhsa_system_sgpr_workgroup_info 0
		.amdhsa_system_vgpr_workitem_id 2
		.amdhsa_next_free_vgpr 256
		.amdhsa_next_free_sgpr 102
		.amdhsa_accum_offset 256
		.amdhsa_reserve_vcc 1
		.amdhsa_float_round_mode_32 0
		.amdhsa_float_round_mode_16_64 0
		.amdhsa_float_denorm_mode_32 3
		.amdhsa_float_denorm_mode_16_64 3
		.amdhsa_dx10_clamp 1
		.amdhsa_ieee_mode 1
		.amdhsa_fp16_overflow 0
		.amdhsa_tg_split 0
		.amdhsa_exception_fp_ieee_invalid_op 0
		.amdhsa_exception_fp_denorm_src 0
		.amdhsa_exception_fp_ieee_div_zero 0
		.amdhsa_exception_fp_ieee_overflow 0
		.amdhsa_exception_fp_ieee_underflow 0
		.amdhsa_exception_fp_ieee_inexact 0
		.amdhsa_exception_int_div_zero 0
	.end_amdhsa_kernel

amdhsa.kernels:
  - .agpr_count:     0
    .args:
      - .offset:         0
        .size:           240
        .value_kind:     by_value
      - .offset:         240
        .size:           4
        .value_kind:     hidden_block_count_x
      - .offset:         244
        .size:           4
        .value_kind:     hidden_block_count_y
      - .offset:         248
        .size:           4
        .value_kind:     hidden_block_count_z
      - .offset:         252
        .size:           2
        .value_kind:     hidden_group_size_x
      - .offset:         254
        .size:           2
        .value_kind:     hidden_group_size_y
      - .offset:         256
        .size:           2
        .value_kind:     hidden_group_size_z
      - .offset:         258
        .size:           2
        .value_kind:     hidden_remainder_x
      - .offset:         260
        .size:           2
        .value_kind:     hidden_remainder_y
      - .offset:         262
        .size:           2
        .value_kind:     hidden_remainder_z
      - .offset:         280
        .size:           8
        .value_kind:     hidden_global_offset_x
      - .offset:         288
        .size:           8
        .value_kind:     hidden_global_offset_y
      - .offset:         296
        .size:           8
        .value_kind:     hidden_global_offset_z
      - .offset:         304
        .size:           2
        .value_kind:     hidden_grid_dims
      - .offset:         328
        .size:           8
        .value_kind:     hidden_multigrid_sync_arg
    .group_segment_fixed_size: 132128
    .kernarg_segment_align: 8
    .kernarg_segment_size: 496
    .language:       OpenCL C
    .language_version:
      - 2
      - 0
    .max_flat_workgroup_size: 512
    .name:           _Z4mega6Params
    .private_segment_fixed_size: 0
    .sgpr_count:     108
    .sgpr_spill_count: 332
    .symbol:         _Z4mega6Params.kd
    .uniform_work_group_size: 1
    .uses_dynamic_stack: false
    .vgpr_count:     256
    .vgpr_spill_count: 0
    .wavefront_size: 64
